# attention epilogue: 8-lane row-stat reductions by DPP adds (quad_perm, quad_perm, row_half_mirror) instead of 3 ds_bpermute round trips each
# speedup vs baseline: 1.0047x; 1.0035x over previous
.LBB0_421:
	s_waitcnt vmcnt(24)
	s_waitcnt vmcnt(9)
	ds_write_b128 v205, v[106:109] offset:32768
	s_waitcnt vmcnt(8)
	ds_write_b128 v205, v[110:113] offset:40960
	v_cmp_gt_u32_e32 vcc, 32, v206
	s_and_saveexec_b64 s[4:5], vcc
	ds_write_b32 v208, v181
	s_or_b64 exec, exec, s[4:5]
	s_waitcnt lgkmcnt(0)
	ds_read_b128 v[50:53], v207
	ds_read_b128 v[54:57], v207 offset:32
	s_lshl_b32 s0, s13, 12
	s_add_i32 s0, s0, 0
	s_add_i32 s0, s0, 0x14800
	s_waitcnt lgkmcnt(1)
	v_rcp_f32_e32 v82, v50
	v_rcp_f32_e32 v83, v51
	v_rcp_f32_e32 v84, v52
	v_rcp_f32_e32 v85, v53
	ds_read_b128 v[50:53], v207 offset:64
	s_waitcnt lgkmcnt(1)
	v_rcp_f32_e32 v86, v54
	v_rcp_f32_e32 v87, v55
	v_rcp_f32_e32 v88, v56
	v_rcp_f32_e32 v89, v57
	ds_read_b128 v[54:57], v207 offset:96
	s_waitcnt lgkmcnt(1)
	v_rcp_f32_e32 v90, v50
	v_rcp_f32_e32 v91, v51
	v_and_b32_e32 v50, 31, v0
	v_lshlrev_b32_e32 v51, 4, v0
	v_lshlrev_b32_e32 v50, 2, v50
	v_add_u32_e32 v178, s0, v51
	v_and_b32_e32 v51, 0xfffffe00, v51
	v_rcp_f32_e32 v92, v52
	v_mul_f32_e32 v52, v66, v82
	v_add3_u32 v179, s0, v50, v51
	v_mul_f32_e32 v50, v67, v83
	v_rcp_f32_e32 v93, v53
	ds_write2_b32 v179, v52, v50 offset1:32
	v_mul_f32_e32 v50, v68, v84
	v_mul_f32_e32 v51, v69, v85
	s_waitcnt lgkmcnt(1)
	v_rcp_f32_e32 v94, v54
	v_rcp_f32_e32 v95, v55
	ds_write2_b32 v179, v50, v51 offset0:64 offset1:96
	v_mul_f32_e32 v50, v70, v86
	v_mul_f32_e32 v51, v71, v87
	v_add_u32_e32 v68, 0x400, v179
	v_rcp_f32_e32 v96, v56
	v_rcp_f32_e32 v97, v57
	ds_write2_b32 v68, v50, v51 offset1:32
	v_mul_f32_e32 v50, v72, v88
	v_mul_f32_e32 v51, v73, v89
	ds_write2_b32 v68, v50, v51 offset0:64 offset1:96
	v_mul_f32_e32 v50, v74, v90
	v_mul_f32_e32 v51, v75, v91
	v_add_u32_e32 v69, 0x800, v179
	ds_write2_b32 v69, v50, v51 offset1:32
	v_mul_f32_e32 v50, v76, v92
	v_mul_f32_e32 v51, v77, v93
	ds_write2_b32 v69, v50, v51 offset0:64 offset1:96
	v_mul_f32_e32 v50, v78, v94
	v_mul_f32_e32 v51, v79, v95
	v_add_u32_e32 v70, 0xc00, v179
	ds_write2_b32 v70, v50, v51 offset1:32
	v_mul_f32_e32 v50, v80, v96
	v_mul_f32_e32 v51, v81, v97
	ds_write2_b32 v70, v50, v51 offset0:64 offset1:96
	s_waitcnt lgkmcnt(0)
	ds_read_b128 v[62:65], v178
	v_lshlrev_b32_e32 v50, 3, v0
	v_and_b32_e32 v71, 56, v50
	v_lshlrev_b32_e32 v50, 16, v176
	v_and_b32_e32 v51, 0xffff0000, v176
	s_waitcnt lgkmcnt(0)
	v_mul_f32_e32 v50, v62, v50
	v_mul_f32_e32 v51, v63, v51
	v_cvt_pk_bf16_f32 v50, v50, v51
	v_lshlrev_b32_e32 v51, 16, v177
	v_and_b32_e32 v52, 0xffff0000, v177
	v_mul_f32_e32 v51, v64, v51
	v_mul_f32_e32 v52, v65, v52
	v_cvt_pk_bf16_f32 v51, v51, v52
	v_add_u32_e32 v52, 64, v0
	v_lshl_add_u32 v72, v52, 4, s0
	ds_read_b128 v[58:61], v72
	v_lshlrev_b32_e32 v53, 8, v0
	v_and_or_b32 v73, v53, s72, v71
	global_store_dwordx2 v73, v[50:51], s[6:7]
	v_lshlrev_b32_e32 v50, 16, v174
	v_and_b32_e32 v51, 0xffff0000, v174
	s_waitcnt lgkmcnt(0)
	v_mul_f32_e32 v50, v58, v50
	v_mul_f32_e32 v51, v59, v51
	v_cvt_pk_bf16_f32 v50, v50, v51
	v_lshlrev_b32_e32 v51, 16, v175
	v_add_u32_e32 v74, 0x80, v0
	v_mul_f32_e32 v51, v60, v51
	v_and_b32_e32 v53, 0xffff0000, v175
	v_lshl_add_u32 v75, v74, 4, s0
	v_mul_f32_e32 v53, v61, v53
	v_cvt_pk_bf16_f32 v51, v51, v53
	ds_read_b128 v[54:57], v75
	v_lshlrev_b32_e32 v52, 8, v52
	v_and_or_b32 v76, v52, s72, v71
	global_store_dwordx2 v76, v[50:51], s[6:7]
	v_lshlrev_b32_e32 v50, 16, v172
	v_and_b32_e32 v51, 0xffff0000, v172
	s_waitcnt lgkmcnt(0)
	v_mul_f32_e32 v50, v54, v50
	v_mul_f32_e32 v51, v55, v51
	v_cvt_pk_bf16_f32 v66, v50, v51
	v_lshlrev_b32_e32 v50, 16, v173
	v_and_b32_e32 v51, 0xffff0000, v173
	v_add_u32_e32 v77, 0xc0, v0
	v_mul_f32_e32 v50, v56, v50
	v_mul_f32_e32 v51, v57, v51
	v_lshl_add_u32 v78, v77, 4, s0
	v_cvt_pk_bf16_f32 v67, v50, v51
	ds_read_b128 v[50:53], v78
	v_lshlrev_b32_e32 v74, 8, v74
	v_and_or_b32 v74, v74, s72, v71
	global_store_dwordx2 v74, v[66:67], s[6:7]
	v_lshlrev_b32_e32 v66, 16, v170
	v_and_b32_e32 v67, 0xffff0000, v170
	s_waitcnt lgkmcnt(0)
	v_mul_f32_e32 v66, v50, v66
	v_mul_f32_e32 v67, v51, v67
	v_cvt_pk_bf16_f32 v66, v66, v67
	v_lshlrev_b32_e32 v67, 16, v171
	v_lshlrev_b32_e32 v77, 8, v77
	v_mul_f32_e32 v67, v52, v67
	v_and_b32_e32 v79, 0xffff0000, v171
	v_and_or_b32 v71, v77, s72, v71
	v_mul_f32_e32 v79, v53, v79
	v_cvt_pk_bf16_f32 v67, v67, v79
	global_store_dwordx2 v71, v[66:67], s[6:7]
	v_mul_f32_e32 v34, v34, v82
	v_mul_f32_e32 v35, v35, v83
	s_waitcnt lgkmcnt(0)
	ds_write2_b32 v179, v34, v35 offset1:32
	v_mul_f32_e32 v34, v36, v84
	v_mul_f32_e32 v35, v37, v85
	ds_write2_b32 v179, v34, v35 offset0:64 offset1:96
	v_mul_f32_e32 v34, v38, v86
	v_mul_f32_e32 v35, v39, v87
	ds_write2_b32 v68, v34, v35 offset1:32
	v_mul_f32_e32 v34, v40, v88
	v_mul_f32_e32 v35, v41, v89
	ds_write2_b32 v68, v34, v35 offset0:64 offset1:96
	v_mul_f32_e32 v34, v42, v90
	v_mul_f32_e32 v35, v43, v91
	ds_write2_b32 v69, v34, v35 offset1:32
	v_mul_f32_e32 v34, v44, v92
	v_mul_f32_e32 v35, v45, v93
	ds_write2_b32 v69, v34, v35 offset0:64 offset1:96
	v_mul_f32_e32 v34, v46, v94
	v_mul_f32_e32 v35, v47, v95
	ds_write2_b32 v70, v34, v35 offset1:32
	v_mul_f32_e32 v34, v48, v96
	v_mul_f32_e32 v35, v49, v97
	ds_write2_b32 v70, v34, v35 offset0:64 offset1:96
	s_waitcnt lgkmcnt(0)
	ds_read_b128 v[46:49], v178
	v_lshlrev_b32_e32 v34, 16, v168
	v_and_b32_e32 v35, 0xffff0000, v168
	v_and_b32_e32 v36, 0xffff0000, v169
	v_mul_f32_e32 v66, v63, v63
	s_waitcnt lgkmcnt(0)
	v_mul_f32_e32 v34, v46, v34
	v_mul_f32_e32 v35, v47, v35
	v_cvt_pk_bf16_f32 v34, v34, v35
	v_lshlrev_b32_e32 v35, 16, v169
	v_mul_f32_e32 v35, v48, v35
	v_mul_f32_e32 v36, v49, v36
	v_cvt_pk_bf16_f32 v35, v35, v36
	ds_read_b128 v[42:45], v72
	global_store_dwordx2 v73, v[34:35], s[6:7] offset:64
	v_lshlrev_b32_e32 v34, 16, v166
	v_and_b32_e32 v35, 0xffff0000, v166
	v_and_b32_e32 v36, 0xffff0000, v167
	s_waitcnt lgkmcnt(0)
	v_mul_f32_e32 v34, v42, v34
	v_mul_f32_e32 v35, v43, v35
	v_cvt_pk_bf16_f32 v34, v34, v35
	v_lshlrev_b32_e32 v35, 16, v167
	v_mul_f32_e32 v35, v44, v35
	v_mul_f32_e32 v36, v45, v36
	v_cvt_pk_bf16_f32 v35, v35, v36
	ds_read_b128 v[38:41], v75
	global_store_dwordx2 v76, v[34:35], s[6:7] offset:64
	v_lshlrev_b32_e32 v34, 16, v164
	v_and_b32_e32 v35, 0xffff0000, v164
	v_fmac_f32_e32 v66, v62, v62
	s_waitcnt lgkmcnt(0)
	v_mul_f32_e32 v34, v38, v34
	v_mul_f32_e32 v35, v39, v35
	v_cvt_pk_bf16_f32 v62, v34, v35
	v_lshlrev_b32_e32 v34, 16, v165
	v_and_b32_e32 v35, 0xffff0000, v165
	v_mul_f32_e32 v34, v40, v34
	v_mul_f32_e32 v35, v41, v35
	v_cvt_pk_bf16_f32 v63, v34, v35
	ds_read_b128 v[34:37], v78
	global_store_dwordx2 v74, v[62:63], s[6:7] offset:64
	v_lshlrev_b32_e32 v62, 16, v162
	v_and_b32_e32 v63, 0xffff0000, v162
	v_mul_f32_e32 v65, v65, v65
	s_waitcnt lgkmcnt(0)
	v_mul_f32_e32 v62, v34, v62
	v_mul_f32_e32 v63, v35, v63
	v_fmac_f32_e32 v65, v64, v64
	v_cvt_pk_bf16_f32 v62, v62, v63
	v_lshlrev_b32_e32 v63, 16, v163
	v_add_f32_e32 v64, v66, v65
	v_mul_f32_e32 v63, v36, v63
	v_and_b32_e32 v65, 0xffff0000, v163
	v_mul_f32_e32 v65, v37, v65
	v_cvt_pk_bf16_f32 v63, v63, v65
	global_store_dwordx2 v71, v[62:63], s[6:7] offset:64
	v_mul_f32_e32 v18, v18, v82
	v_mul_f32_e32 v19, v19, v83
	s_waitcnt lgkmcnt(0)
	ds_write2_b32 v179, v18, v19 offset1:32
	v_mul_f32_e32 v18, v20, v84
	v_mul_f32_e32 v19, v21, v85
	ds_write2_b32 v179, v18, v19 offset0:64 offset1:96
	v_mul_f32_e32 v18, v22, v86
	v_mul_f32_e32 v19, v23, v87
	ds_write2_b32 v68, v18, v19 offset1:32
	v_mul_f32_e32 v18, v24, v88
	v_mul_f32_e32 v19, v25, v89
	ds_write2_b32 v68, v18, v19 offset0:64 offset1:96
	v_mul_f32_e32 v18, v26, v90
	v_mul_f32_e32 v19, v27, v91
	ds_write2_b32 v69, v18, v19 offset1:32
	v_mul_f32_e32 v18, v28, v92
	v_mul_f32_e32 v19, v29, v93
	ds_write2_b32 v69, v18, v19 offset0:64 offset1:96
	v_mul_f32_e32 v18, v30, v94
	v_mul_f32_e32 v19, v31, v95
	ds_write2_b32 v70, v18, v19 offset1:32
	v_mul_f32_e32 v18, v32, v96
	v_mul_f32_e32 v19, v33, v97
	ds_write2_b32 v70, v18, v19 offset0:64 offset1:96
	s_waitcnt lgkmcnt(0)
	ds_read_b128 v[30:33], v178
	s_waitcnt vmcnt(15)
	v_lshlrev_b32_e32 v18, 16, v128
	v_and_b32_e32 v19, 0xffff0000, v128
	v_and_b32_e32 v22, 0xffff0000, v129
	v_mul_f32_e32 v20, v47, v47
	s_waitcnt lgkmcnt(0)
	v_mul_f32_e32 v18, v30, v18
	v_mul_f32_e32 v19, v31, v19
	v_cvt_pk_bf16_f32 v18, v18, v19
	v_lshlrev_b32_e32 v19, 16, v129
	v_mul_f32_e32 v19, v32, v19
	v_mul_f32_e32 v22, v33, v22
	v_cvt_pk_bf16_f32 v19, v19, v22
	ds_read_b128 v[26:29], v72
	global_store_dwordx2 v73, v[18:19], s[6:7] offset:128
	s_waitcnt vmcnt(15)
	v_lshlrev_b32_e32 v18, 16, v126
	v_and_b32_e32 v19, 0xffff0000, v126
	v_mul_f32_e32 v21, v49, v49
	s_waitcnt lgkmcnt(0)
	v_mul_f32_e32 v18, v26, v18
	v_mul_f32_e32 v19, v27, v19
	v_fmac_f32_e32 v20, v46, v46
	v_fmac_f32_e32 v21, v48, v48
	v_cvt_pk_bf16_f32 v18, v18, v19
	v_lshlrev_b32_e32 v19, 16, v127
	v_add_f32_e32 v20, v20, v21
	v_mul_f32_e32 v19, v28, v19
	v_and_b32_e32 v21, 0xffff0000, v127
	v_mul_f32_e32 v21, v29, v21
	v_cvt_pk_bf16_f32 v19, v19, v21
	ds_read_b128 v[22:25], v75
	global_store_dwordx2 v76, v[18:19], s[6:7] offset:128
	s_waitcnt vmcnt(15)
	v_lshlrev_b32_e32 v18, 16, v124
	v_and_b32_e32 v19, 0xffff0000, v124
	v_add_f32_e32 v48, v64, v20
	s_waitcnt lgkmcnt(0)
	v_mul_f32_e32 v18, v22, v18
	v_mul_f32_e32 v19, v23, v19
	v_cvt_pk_bf16_f32 v46, v18, v19
	v_lshlrev_b32_e32 v18, 16, v125
	v_and_b32_e32 v19, 0xffff0000, v125
	v_mul_f32_e32 v18, v24, v18
	v_mul_f32_e32 v19, v25, v19
	v_cvt_pk_bf16_f32 v47, v18, v19
	ds_read_b128 v[18:21], v78
	v_mul_f32_e32 v49, v31, v31
	v_fmac_f32_e32 v49, v30, v30
	s_waitcnt vmcnt(14)
	v_lshlrev_b32_e32 v30, 16, v122
	v_and_b32_e32 v31, 0xffff0000, v122
	s_waitcnt lgkmcnt(0)
	v_mul_f32_e32 v30, v18, v30
	v_mul_f32_e32 v31, v19, v31
	global_store_dwordx2 v74, v[46:47], s[6:7] offset:128
	v_cvt_pk_bf16_f32 v30, v30, v31
	v_lshlrev_b32_e32 v31, 16, v123
	v_mul_f32_e32 v31, v20, v31
	v_and_b32_e32 v46, 0xffff0000, v123
	v_mul_f32_e32 v46, v21, v46
	v_cvt_pk_bf16_f32 v31, v31, v46
	global_store_dwordx2 v71, v[30:31], s[6:7] offset:128
	v_mul_f32_e32 v2, v2, v82
	v_mul_f32_e32 v3, v3, v83
	s_waitcnt lgkmcnt(0)
	ds_write2_b32 v179, v2, v3 offset1:32
	v_mul_f32_e32 v2, v4, v84
	v_mul_f32_e32 v3, v5, v85
	ds_write2_b32 v179, v2, v3 offset0:64 offset1:96
	v_mul_f32_e32 v2, v6, v86
	v_mul_f32_e32 v3, v7, v87
	ds_write2_b32 v68, v2, v3 offset1:32
	v_mul_f32_e32 v2, v8, v88
	v_mul_f32_e32 v3, v9, v89
	ds_write2_b32 v68, v2, v3 offset0:64 offset1:96
	v_mul_f32_e32 v2, v10, v90
	v_mul_f32_e32 v3, v11, v91
	ds_write2_b32 v69, v2, v3 offset1:32
	v_mul_f32_e32 v2, v12, v92
	v_mul_f32_e32 v3, v13, v93
	ds_write2_b32 v69, v2, v3 offset0:64 offset1:96
	v_mul_f32_e32 v2, v14, v94
	v_mul_f32_e32 v3, v15, v95
	ds_write2_b32 v70, v2, v3 offset1:32
	v_mul_f32_e32 v2, v16, v96
	v_mul_f32_e32 v3, v17, v97
	ds_write2_b32 v70, v2, v3 offset0:64 offset1:96
	s_waitcnt lgkmcnt(0)
	ds_read_b128 v[2:5], v178
	v_mul_f32_e32 v33, v33, v33
	v_fmac_f32_e32 v33, v32, v32
	v_add_f32_e32 v6, v49, v33
	v_add_f32_e32 v16, v48, v6
	s_waitcnt vmcnt(15)
	v_lshlrev_b32_e32 v6, 16, v120
	v_and_b32_e32 v7, 0xffff0000, v120
	s_waitcnt lgkmcnt(0)
	v_mul_f32_e32 v6, v2, v6
	v_mul_f32_e32 v7, v3, v7
	v_cvt_pk_bf16_f32 v6, v6, v7
	v_lshlrev_b32_e32 v7, 16, v121
	v_mul_f32_e32 v7, v4, v7
	v_and_b32_e32 v8, 0xffff0000, v121
	v_mul_f32_e32 v8, v5, v8
	v_cvt_pk_bf16_f32 v7, v7, v8
	ds_read_b128 v[10:13], v72
	v_mul_f32_e32 v17, v3, v3
	v_fmac_f32_e32 v17, v2, v2
	s_waitcnt vmcnt(14)
	v_lshlrev_b32_e32 v2, 16, v118
	v_and_b32_e32 v3, 0xffff0000, v118
	s_waitcnt lgkmcnt(0)
	v_mul_f32_e32 v2, v10, v2
	v_mul_f32_e32 v3, v11, v3
	global_store_dwordx2 v73, v[6:7], s[6:7] offset:192
	v_cvt_pk_bf16_f32 v2, v2, v3
	v_lshlrev_b32_e32 v3, 16, v119
	v_and_b32_e32 v6, 0xffff0000, v119
	v_mul_f32_e32 v3, v12, v3
	v_mul_f32_e32 v6, v13, v6
	v_cvt_pk_bf16_f32 v3, v3, v6
	ds_read_b128 v[6:9], v75
	global_store_dwordx2 v76, v[2:3], s[6:7] offset:192
	s_waitcnt vmcnt(15)
	v_lshlrev_b32_e32 v2, 16, v116
	v_and_b32_e32 v3, 0xffff0000, v116
	v_mul_f32_e32 v30, v5, v5
	s_waitcnt lgkmcnt(0)
	v_mul_f32_e32 v2, v6, v2
	v_mul_f32_e32 v3, v7, v3
	v_cvt_pk_bf16_f32 v14, v2, v3
	v_lshlrev_b32_e32 v2, 16, v117
	v_and_b32_e32 v3, 0xffff0000, v117
	v_mul_f32_e32 v2, v8, v2
	v_mul_f32_e32 v3, v9, v3
	v_fmac_f32_e32 v30, v4, v4
	v_cvt_pk_bf16_f32 v15, v2, v3
	ds_read_b128 v[2:5], v78
	global_store_dwordx2 v74, v[14:15], s[6:7] offset:192
	s_waitcnt vmcnt(15)
	v_lshlrev_b32_e32 v14, 16, v114
	v_and_b32_e32 v15, 0xffff0000, v114
	v_add_f32_e32 v17, v17, v30
	s_waitcnt lgkmcnt(0)
	v_mul_f32_e32 v14, v2, v14
	v_mul_f32_e32 v15, v3, v15
	v_cvt_pk_bf16_f32 v14, v14, v15
	v_lshlrev_b32_e32 v15, 16, v115
	v_add_f32_e32 v30, v16, v17
	v_mul_f32_e32 v15, v4, v15
	v_and_b32_e32 v16, 0xffff0000, v115
	v_mul_f32_e32 v16, v5, v16
	v_cvt_pk_bf16_f32 v15, v15, v16
	global_store_dwordx2 v71, v[14:15], s[6:7] offset:192
	s_waitcnt lgkmcnt(0)
	s_nop 1
	v_add_f32_dpp v14, v30, v30 quad_perm:[1,0,3,2] row_mask:0xf bank_mask:0xf
	s_nop 1
	v_add_f32_dpp v31, v14, v14 quad_perm:[2,3,0,1] row_mask:0xf bank_mask:0xf
	s_nop 1
	v_add_f32_dpp v32, v31, v31 row_half_mirror row_mask:0xf bank_mask:0xf
	s_lshl_b64 s[0:1], s[48:49], 2
	s_add_u32 s4, s18, s0
	s_addc_u32 s5, s19, s1
	v_and_b32_e32 v14, 7, v0
	v_cmp_eq_u32_e32 vcc, 0, v14
	v_ashrrev_i32_e32 v14, 3, v0
	v_ashrrev_i32_e32 v15, 31, v14
	s_and_saveexec_b64 s[6:7], vcc
	s_cbranch_execz .LBB0_425
	v_lshl_add_u64 v[46:47], v[14:15], 2, s[4:5]
	s_waitcnt lgkmcnt(0)
	v_mov_b32_e32 v0, v32
	global_store_dword v[46:47], v0, off
.LBB0_425:
	s_or_b64 exec, exec, s[6:7]
	v_mul_f32_e32 v0, v59, v59
	v_mul_f32_e32 v31, v61, v61
	v_fmac_f32_e32 v0, v58, v58
	v_fmac_f32_e32 v31, v60, v60
	v_add_f32_e32 v0, v0, v31
	v_mul_f32_e32 v31, v43, v43
	s_waitcnt lgkmcnt(0)
	v_mul_f32_e32 v32, v45, v45
	v_mul_f32_e32 v27, v27, v27
	v_fmac_f32_e32 v31, v42, v42
	v_fmac_f32_e32 v32, v44, v44
	v_fmac_f32_e32 v27, v26, v26
	v_mul_f32_e32 v26, v29, v29
	v_mul_f32_e32 v11, v11, v11
	v_add_f32_e32 v31, v31, v32
	v_fmac_f32_e32 v26, v28, v28
	v_fmac_f32_e32 v11, v10, v10
	v_mul_f32_e32 v10, v13, v13
	v_add_f32_e32 v0, v0, v31
	v_add_f32_e32 v26, v27, v26
	v_fmac_f32_e32 v10, v12, v12
	v_add_f32_e32 v0, v0, v26
	v_add_f32_e32 v10, v11, v10
	v_add_f32_e32 v0, v0, v10
	s_nop 1
	v_add_f32_dpp v0, v0, v0 quad_perm:[1,0,3,2] row_mask:0xf bank_mask:0xf
	s_nop 1
	v_add_f32_dpp v0, v0, v0 quad_perm:[2,3,0,1] row_mask:0xf bank_mask:0xf
	s_nop 1
	v_add_f32_dpp v10, v0, v0 row_half_mirror row_mask:0xf bank_mask:0xf
	s_and_saveexec_b64 s[6:7], vcc
	s_cbranch_execz .LBB0_427
	v_lshl_add_u64 v[12:13], v[14:15], 2, s[4:5]
	s_waitcnt lgkmcnt(0)
	v_mov_b32_e32 v0, v10
	global_store_dword v[12:13], v0, off offset:32
.LBB0_427:
	s_or_b64 exec, exec, s[6:7]
	v_mul_f32_e32 v0, v55, v55
	s_waitcnt lgkmcnt(0)
	v_mul_f32_e32 v10, v57, v57
	v_fmac_f32_e32 v0, v54, v54
	v_fmac_f32_e32 v10, v56, v56
	v_add_f32_e32 v0, v0, v10
	v_mul_f32_e32 v10, v39, v39
	v_mul_f32_e32 v11, v41, v41
	v_fmac_f32_e32 v10, v38, v38
	v_fmac_f32_e32 v11, v40, v40
	v_add_f32_e32 v10, v10, v11
	v_add_f32_e32 v0, v0, v10
	v_mul_f32_e32 v10, v23, v23
	v_mul_f32_e32 v11, v25, v25
	v_mul_f32_e32 v7, v7, v7
	v_fmac_f32_e32 v10, v22, v22
	v_fmac_f32_e32 v11, v24, v24
	v_fmac_f32_e32 v7, v6, v6
	v_mul_f32_e32 v6, v9, v9
	v_add_f32_e32 v10, v10, v11
	v_fmac_f32_e32 v6, v8, v8
	v_add_f32_e32 v0, v0, v10
	v_add_f32_e32 v6, v7, v6
	v_add_f32_e32 v0, v0, v6
	s_nop 1
	v_add_f32_dpp v0, v0, v0 quad_perm:[1,0,3,2] row_mask:0xf bank_mask:0xf
	s_nop 1
	v_add_f32_dpp v0, v0, v0 quad_perm:[2,3,0,1] row_mask:0xf bank_mask:0xf
	s_nop 1
	v_add_f32_dpp v6, v0, v0 row_half_mirror row_mask:0xf bank_mask:0xf
	s_and_saveexec_b64 s[6:7], vcc
	s_cbranch_execz .LBB0_429
	v_lshl_add_u64 v[8:9], v[14:15], 2, s[4:5]
	s_waitcnt lgkmcnt(0)
	v_mov_b32_e32 v0, v6
	global_store_dword v[8:9], v0, off offset:64
.LBB0_429:
	s_or_b64 exec, exec, s[6:7]
	v_mul_f32_e32 v0, v51, v51
	s_waitcnt lgkmcnt(0)
	v_mul_f32_e32 v6, v53, v53
	v_fmac_f32_e32 v0, v50, v50
	v_fmac_f32_e32 v6, v52, v52
	v_add_f32_e32 v0, v0, v6
	v_mul_f32_e32 v6, v35, v35
	v_mul_f32_e32 v7, v37, v37
	v_fmac_f32_e32 v6, v34, v34
	v_fmac_f32_e32 v7, v36, v36
	v_add_f32_e32 v6, v6, v7
	v_add_f32_e32 v0, v0, v6
	v_mul_f32_e32 v6, v19, v19
	v_mul_f32_e32 v7, v21, v21
	v_mul_f32_e32 v3, v3, v3
	v_fmac_f32_e32 v6, v18, v18
	v_fmac_f32_e32 v7, v20, v20
	v_fmac_f32_e32 v3, v2, v2
	v_mul_f32_e32 v2, v5, v5
	v_add_f32_e32 v6, v6, v7
	v_fmac_f32_e32 v2, v4, v4
	v_add_f32_e32 v0, v0, v6
	v_add_f32_e32 v2, v3, v2
	v_add_f32_e32 v0, v0, v2
	s_nop 1
	v_add_f32_dpp v0, v0, v0 quad_perm:[1,0,3,2] row_mask:0xf bank_mask:0xf
	s_nop 1
	v_add_f32_dpp v0, v0, v0 quad_perm:[2,3,0,1] row_mask:0xf bank_mask:0xf
	s_nop 1
	v_add_f32_dpp v2, v0, v0 row_half_mirror row_mask:0xf bank_mask:0xf
	s_and_saveexec_b64 s[6:7], vcc
	s_cbranch_execz .LBB0_372
	v_lshl_add_u64 v[4:5], v[14:15], 2, s[4:5]
	s_waitcnt lgkmcnt(0)
	v_mov_b32_e32 v0, v2
	global_store_dword v[4:5], v0, off offset:96
	s_branch .LBB0_372
